# gMLP tile-0 LayerNorm A-fragment build: 48 LDS reads batched per k-step instead of 16 serial read-wait groups (bit-identical math)
# speedup vs baseline: 1.0245x; 1.0012x over previous
; #define LAS __attribute__((address_space(3)))
; __device__ __forceinline__ bf16x8 pack8(f32x4 lo, f32x4 hi) { v4u w; w.x = pk2(lo[0], lo[1]); w.y = pk2(lo[2], lo[3]); w.z = pk2(hi[0], hi[1]); w.w = pk2(hi[2], hi[3]); return __builtin_bit_cast(bf16x8, w); }
; __device__ __forceinline__ void gmlp_compute(GmlpRegs& R, const Args& a, const Ctx& C, int c, int hd) {
;     ...
; #pragma unroll
;     for (int ks = 0; ks < 4; ++ks) { f32x4 lo, hi;
; #pragma unroll
;         for (int e = 0; e < 8; ++e) { const int sl = 32 * ks + 8 * q + e;
;             const float v = __uint_as_float((unsigned)*(const LAS unsigned short*)(VL + sl * 260 + (16 * w + fr) * 2) << 16);
;             const float x = (v - ST[2 * sl]) * ST[2 * sl + 1] * lg + lb; if (e < 4) lo[e] = x; else hi[e - 4] = x; }
;         af[ks] = pack8(lo, hi); }
.LBB0_971:
	s_or_b64 exec, exec, s[76:77]
	v_or_b32_e32 v144, s2, v149
	v_lshrrev_b32_e32 v145, 4, v162
	v_lshl_add_u32 v165, v144, 1, 0
	s_movk_i32 s74, 0x820
	v_mad_u32_u24 v62, v145, s74, v165
	s_waitcnt lgkmcnt(0)
	s_barrier
	v_lshlrev_b32_e32 v63, 6, v145
	s_add_i32 s2, 0, 0x10a00
	v_add_u32_e32 v183, s2, v63
	v_lshlrev_b32_e32 v153, 3, v145
	v_or_b32_e32 v64, 2, v153
	s_waitcnt vmcnt(28)
	v_mov_b32_e32 v99, v98
	v_lshlrev_b32_e32 v52, 3, v64
	v_add_u32_e32 v168, s2, v52
	v_mov_b32_e32 v101, v100
	v_mul_u32_u24_e32 v167, 0x104, v64
	s_mov_b32 s74, 0x18000
	s_mov_b32 s75, 0x20000
	s_mov_b32 s76, 0x28000
	s_mov_b32 s77, 0x30000
	v_or_b32_e32 v52, 32, v63
	v_add_u32_e32 v163, s2, v52
	s_mov_b32 s78, 0x38000
	v_mul_u32_u24_e32 v184, 0x820, v145
	v_mul_u32_u24_e32 v200, 0x110, v149
	s_nop 0
	v_or_b32_e32 v52, 48, v63
	v_add_u32_e32 v166, s2, v52
	s_nop 0
	v_or_b32_e32 v54, 0x100, v63
	v_add_u32_e32 v185, s2, v54
	s_nop 0
	v_or_b32_e32 v54, 0x110, v63
	v_add_u32_e32 v186, s2, v54
	v_or_b32_e32 v65, 0x220, v63
	v_add_u32_e32 v192, s2, v65
	s_nop 0
	v_or_b32_e32 v54, 0x120, v63
	v_add_u32_e32 v188, s2, v54
	v_mov_b32_e32 v54, 0x2288
	v_mad_u32_u24 v54, v64, s33, v54
	v_add_u32_e32 v187, v165, v54
	s_nop 0
	v_or_b32_e32 v54, 0x130, v63
	v_add_u32_e32 v189, s2, v54
	v_or_b32_e32 v58, 0x200, v63
	v_add_u32_e32 v190, s2, v58
	v_or_b32_e32 v60, 0x210, v63
	v_add_u32_e32 v191, s2, v60
	v_or_b32_e32 v65, 0x230, v63
	v_add_u32_e32 v194, s2, v65
	v_mov_b32_e32 v65, 0x4510
	v_mad_u32_u24 v64, v64, s33, v65
	v_add_u32_e32 v193, v165, v64
	s_mov_b32 s33, 0x10000
	s_nop 0
	v_or_b32_e32 v64, 0x300, v63
	v_add_u32_e32 v195, s2, v64
	s_nop 0
	v_or_b32_e32 v64, 0x310, v63
	v_add_u32_e32 v196, s2, v64
	s_nop 0
	v_or_b32_e32 v64, 0x320, v63
	v_add_u32_e32 v197, s2, v64
	v_or_b32_e32 v63, 0x330, v63
	v_add_u32_e32 v198, s2, v63
	s_mov_b32 s2, 0x8000
	v_and_b32_e32 v66, 48, v0
	v_add_u32_e32 v199, 0, v66
	v_mad_u32_u24 v112, v149, s1, v199
	v_lshlrev_b32_e32 v82, 6, v145
	v_add_u32_e32 v82, 0x10a00, v82
	ds_read_u16 v66, v62 offset:34816
	ds_read_u16 v67, v62 offset:35076
	ds_read_u16 v68, v62 offset:35336
	ds_read_u16 v69, v62 offset:35596
	ds_read_u16 v70, v62 offset:35856
	ds_read_u16 v71, v62 offset:36116
	ds_read_u16 v72, v62 offset:36376
	ds_read_u16 v73, v62 offset:36636
	ds_read_b128 v[204:207], v82
	ds_read_b128 v[208:211], v82 offset:16
	ds_read_b128 v[212:215], v82 offset:32
	ds_read_b128 v[216:219], v82 offset:48
	ds_read_u16 v74, v62 offset:43136
	ds_read_u16 v75, v62 offset:43396
	ds_read_u16 v76, v62 offset:43656
	ds_read_u16 v77, v62 offset:43916
	ds_read_u16 v78, v62 offset:44176
	ds_read_u16 v79, v62 offset:44436
	ds_read_u16 v80, v62 offset:44696
	ds_read_u16 v81, v62 offset:44956
	ds_read_b128 v[220:223], v82 offset:256
	ds_read_b128 v[224:227], v82 offset:272
	ds_read_b128 v[228:231], v82 offset:288
	ds_read_b128 v[232:235], v82 offset:304
	s_waitcnt lgkmcnt(12)
	v_lshlrev_b32_e32 v66, 16, v66
	v_lshlrev_b32_e32 v67, 16, v67
	v_lshlrev_b32_e32 v68, 16, v68
	v_lshlrev_b32_e32 v69, 16, v69
	v_lshlrev_b32_e32 v70, 16, v70
	v_lshlrev_b32_e32 v71, 16, v71
	v_lshlrev_b32_e32 v72, 16, v72
	v_lshlrev_b32_e32 v73, 16, v73
	v_sub_f32_e32 v66, v66, v204
	v_sub_f32_e32 v67, v67, v206
	v_sub_f32_e32 v68, v68, v208
	v_sub_f32_e32 v69, v69, v210
	v_sub_f32_e32 v70, v70, v212
	v_sub_f32_e32 v71, v71, v214
	v_sub_f32_e32 v72, v72, v216
	v_sub_f32_e32 v73, v73, v218
	v_mul_f32_e32 v66, v205, v66
	v_mul_f32_e32 v67, v207, v67
	v_mul_f32_e32 v68, v209, v68
	v_mul_f32_e32 v69, v211, v69
	v_mul_f32_e32 v70, v213, v70
	v_mul_f32_e32 v71, v215, v71
	v_mul_f32_e32 v72, v217, v72
	v_mul_f32_e32 v73, v219, v73
	v_fma_f32 v66, v98, v66, v100
	v_fma_f32 v67, v98, v67, v100
	v_fma_f32 v68, v98, v68, v100
	v_fma_f32 v69, v98, v69, v100
	v_fma_f32 v70, v98, v70, v100
	v_fma_f32 v71, v98, v71, v100
	v_fma_f32 v72, v98, v72, v100
	v_fma_f32 v73, v98, v73, v100
	v_cvt_pk_bf16_f32 v50, v66, v67
	v_cvt_pk_bf16_f32 v51, v68, v69
	v_cvt_pk_bf16_f32 v52, v70, v71
	v_cvt_pk_bf16_f32 v53, v72, v73
	ds_read_u16 v66, v62 offset:51456
	ds_read_u16 v67, v62 offset:51716
	ds_read_u16 v68, v62 offset:51976
	ds_read_u16 v69, v62 offset:52236
	ds_read_u16 v70, v62 offset:52496
	ds_read_u16 v71, v62 offset:52756
	ds_read_u16 v72, v62 offset:53016
	ds_read_u16 v73, v62 offset:53276
	ds_read_b128 v[204:207], v82 offset:512
	ds_read_b128 v[208:211], v82 offset:528
	ds_read_b128 v[212:215], v82 offset:544
	ds_read_b128 v[216:219], v82 offset:560
	s_waitcnt lgkmcnt(12)
	v_lshlrev_b32_e32 v74, 16, v74
	v_lshlrev_b32_e32 v75, 16, v75
	v_lshlrev_b32_e32 v76, 16, v76
	v_lshlrev_b32_e32 v77, 16, v77
	v_lshlrev_b32_e32 v78, 16, v78
	v_lshlrev_b32_e32 v79, 16, v79
	v_lshlrev_b32_e32 v80, 16, v80
	v_lshlrev_b32_e32 v81, 16, v81
	v_sub_f32_e32 v74, v74, v220
	v_sub_f32_e32 v75, v75, v222
	v_sub_f32_e32 v76, v76, v224
	v_sub_f32_e32 v77, v77, v226
	v_sub_f32_e32 v78, v78, v228
	v_sub_f32_e32 v79, v79, v230
	v_sub_f32_e32 v80, v80, v232
	v_sub_f32_e32 v81, v81, v234
	v_mul_f32_e32 v74, v221, v74
	v_mul_f32_e32 v75, v223, v75
	v_mul_f32_e32 v76, v225, v76
	v_mul_f32_e32 v77, v227, v77
	v_mul_f32_e32 v78, v229, v78
	v_mul_f32_e32 v79, v231, v79
	v_mul_f32_e32 v80, v233, v80
	v_mul_f32_e32 v81, v235, v81
	v_fma_f32 v74, v98, v74, v100
	v_fma_f32 v75, v98, v75, v100
	v_fma_f32 v76, v98, v76, v100
	v_fma_f32 v77, v98, v77, v100
	v_fma_f32 v78, v98, v78, v100
	v_fma_f32 v79, v98, v79, v100
	v_fma_f32 v80, v98, v80, v100
	v_fma_f32 v81, v98, v81, v100
	v_cvt_pk_bf16_f32 v54, v74, v75
	v_cvt_pk_bf16_f32 v55, v76, v77
	v_cvt_pk_bf16_f32 v56, v78, v79
	v_cvt_pk_bf16_f32 v57, v80, v81
	ds_read_u16 v74, v62 offset:59776
	ds_read_u16 v75, v62 offset:60036
	ds_read_u16 v76, v62 offset:60296
	ds_read_u16 v77, v62 offset:60556
	ds_read_u16 v78, v62 offset:60816
	ds_read_u16 v79, v62 offset:61076
	ds_read_u16 v80, v62 offset:61336
	ds_read_u16 v81, v62 offset:61596
	ds_read_b128 v[220:223], v82 offset:768
	ds_read_b128 v[224:227], v82 offset:784
	ds_read_b128 v[228:231], v82 offset:800
	ds_read_b128 v[232:235], v82 offset:816
	s_waitcnt lgkmcnt(12)
; #define LAS __attribute__((address_space(3)))
; #define MFMA16(A, B, Cc) __builtin_amdgcn_mfma_f32_16x16x32_bf16((A), (B), (Cc), 0, 0, 0)
; #define PIN(x) asm volatile("" : "+v"(x))
; __device__ __forceinline__ float bf_lo(unsigned w) { return __uint_as_float(w << 16); }
; __device__ __forceinline__ unsigned pk4f8(float a, float b, float c, float d) { int p = __builtin_amdgcn_cvt_pk_fp8_f32(sat8(a), sat8(b), 0, false); p = __builtin_amdgcn_cvt_pk_fp8_f32(sat8(c), sat8(d), p, true); return (unsigned)p; }
; __device__ __forceinline__ float bf_hi(unsigned w) { return __uint_as_float(w & 0xffff0000u); }
; __device__ __forceinline__ bf16x8 pack8(f32x4 lo, f32x4 hi) { v4u w; w.x = pk2(lo[0], lo[1]); w.y = pk2(lo[2], lo[3]); w.z = pk2(hi[0], hi[1]); w.w = pk2(hi[2], hi[3]); return __builtin_bit_cast(bf16x8, w); }
; __device__ __forceinline__ void gmlp_compute(GmlpRegs& R, const Args& a, const Ctx& C, int c, int hd) {
;     ...
; #pragma unroll
;     for (int ks = 0; ks < 4; ++ks) { f32x4 lo, hi;
; #pragma unroll
;         for (int e = 0; e < 8; ++e) { const int sl = 32 * ks + 8 * q + e;
;             const float v = __uint_as_float((unsigned)*(const LAS unsigned short*)(VL + sl * 260 + (16 * w + fr) * 2) << 16);
;             const float x = (v - ST[2 * sl]) * ST[2 * sl + 1] * lg + lb; if (e < 4) lo[e] = x; else hi[e - 4] = x; }
;         af[ks] = pack8(lo, hi); }
;     f32x4 acc[8];
; #pragma unroll
;     for (int nt = 0; nt < 8; ++nt) { acc[nt] = (f32x4){0.f, 0.f, 0.f, 0.f};
; #pragma unroll
;         for (int ks = 0; ks <= nt / 2; ++ks) acc[nt] = MFMA16(af[ks], *(const LAS bf16x8*)(WL + (16 * nt + fr) * 272 + (32 * ks + 8 * q) * 2), acc[nt]); }
; #pragma unroll
;     for (int nt = 0; nt < 8; ++nt) PIN(R.uq[nt]);
; #pragma unroll
;     for (int nt = 0; nt < 8; ++nt) { const size_t row = T0 + 16 * nt + fr; const float bs = R.bsv[nt];
;         const float o0 = bf_lo(R.uq[nt].x) * (acc[nt][0] + bs), o1 = bf_hi(R.uq[nt].x) * (acc[nt][1] + bs);
;         const float o2 = bf_lo(R.uq[nt].y) * (acc[nt][2] + bs), o3 = bf_hi(R.uq[nt].y) * (acc[nt][3] + bs);
;         *(unsigned*)((unsigned char*)Y + row * DM + chs) = pk4f8(o0, o1, o2, o3); }
	v_lshlrev_b32_e32 v66, 16, v66
	v_lshlrev_b32_e32 v67, 16, v67
	v_lshlrev_b32_e32 v68, 16, v68
	v_lshlrev_b32_e32 v69, 16, v69
	v_lshlrev_b32_e32 v70, 16, v70
	v_lshlrev_b32_e32 v71, 16, v71
	v_lshlrev_b32_e32 v72, 16, v72
	v_lshlrev_b32_e32 v73, 16, v73
	v_sub_f32_e32 v66, v66, v204
	v_sub_f32_e32 v67, v67, v206
	v_sub_f32_e32 v68, v68, v208
	v_sub_f32_e32 v69, v69, v210
	v_sub_f32_e32 v70, v70, v212
	v_sub_f32_e32 v71, v71, v214
	v_sub_f32_e32 v72, v72, v216
	v_sub_f32_e32 v73, v73, v218
	v_mul_f32_e32 v66, v205, v66
	v_mul_f32_e32 v67, v207, v67
	v_mul_f32_e32 v68, v209, v68
	v_mul_f32_e32 v69, v211, v69
	v_mul_f32_e32 v70, v213, v70
	v_mul_f32_e32 v71, v215, v71
	v_mul_f32_e32 v72, v217, v72
	v_mul_f32_e32 v73, v219, v73
	v_fma_f32 v66, v98, v66, v100
	v_fma_f32 v67, v98, v67, v100
	v_fma_f32 v68, v98, v68, v100
	v_fma_f32 v69, v98, v69, v100
	v_fma_f32 v70, v98, v70, v100
	v_fma_f32 v71, v98, v71, v100
	v_fma_f32 v72, v98, v72, v100
	v_fma_f32 v73, v98, v73, v100
	v_cvt_pk_bf16_f32 v58, v66, v67
	v_cvt_pk_bf16_f32 v59, v68, v69
	v_cvt_pk_bf16_f32 v60, v70, v71
	v_cvt_pk_bf16_f32 v61, v72, v73
	s_waitcnt lgkmcnt(0)
	v_lshlrev_b32_e32 v74, 16, v74
	v_lshlrev_b32_e32 v75, 16, v75
	v_lshlrev_b32_e32 v76, 16, v76
	v_lshlrev_b32_e32 v77, 16, v77
	v_lshlrev_b32_e32 v78, 16, v78
	v_lshlrev_b32_e32 v79, 16, v79
	v_lshlrev_b32_e32 v80, 16, v80
	v_lshlrev_b32_e32 v81, 16, v81
	v_sub_f32_e32 v74, v74, v220
	v_sub_f32_e32 v75, v75, v222
	v_sub_f32_e32 v76, v76, v224
	v_sub_f32_e32 v77, v77, v226
	v_sub_f32_e32 v78, v78, v228
	v_sub_f32_e32 v79, v79, v230
	v_sub_f32_e32 v80, v80, v232
	v_sub_f32_e32 v81, v81, v234
	v_mul_f32_e32 v74, v221, v74
	v_mul_f32_e32 v75, v223, v75
	v_mul_f32_e32 v76, v225, v76
	v_mul_f32_e32 v77, v227, v77
	v_mul_f32_e32 v78, v229, v78
	v_mul_f32_e32 v79, v231, v79
	v_mul_f32_e32 v80, v233, v80
	v_mul_f32_e32 v81, v235, v81
	v_fma_f32 v74, v98, v74, v100
	v_fma_f32 v75, v98, v75, v100
	v_fma_f32 v76, v98, v76, v100
	v_fma_f32 v77, v98, v77, v100
	v_fma_f32 v78, v98, v78, v100
	v_fma_f32 v79, v98, v79, v100
	v_fma_f32 v80, v98, v80, v100
	v_fma_f32 v81, v98, v81, v100
	v_cvt_pk_bf16_f32 v62, v74, v75
	v_cvt_pk_bf16_f32 v63, v76, v77
	v_cvt_pk_bf16_f32 v64, v78, v79
	v_cvt_pk_bf16_f32 v65, v80, v81
	ds_read_b128 v[66:69], v112
	ds_read_b128 v[70:73], v112 offset:8704
	s_waitcnt lgkmcnt(1)
	v_mfma_f32_16x16x32_bf16 v[78:81], v[50:53], v[66:69], 0
	ds_read_b128 v[66:69], v112 offset:4352
	ds_read_b128 v[74:77], v112 offset:8768
	ds_read_b128 v[82:85], v112 offset:13120
	s_waitcnt lgkmcnt(3)
	v_mfma_f32_16x16x32_bf16 v[70:73], v[50:53], v[70:73], 0
	ds_read_b128 v[86:89], v112 offset:17472
	ds_read_b128 v[90:93], v112 offset:21824
	ds_read_b128 v[202:205], v112 offset:26176
	s_waitcnt lgkmcnt(4)
	v_mfma_f32_16x16x32_bf16 v[70:73], v[54:57], v[74:77], v[70:73]
	ds_read_b128 v[74:77], v112 offset:13056
	s_mov_b32 s1, 0xc3e00000
	s_waitcnt lgkmcnt(0)
	v_mfma_f32_16x16x32_bf16 v[74:77], v[50:53], v[74:77], 0
	v_mfma_f32_16x16x32_bf16 v[74:77], v[54:57], v[82:85], v[74:77]
	ds_read_b128 v[82:85], v112 offset:17408
	s_waitcnt lgkmcnt(0)
	v_mfma_f32_16x16x32_bf16 v[82:85], v[50:53], v[82:85], 0
	v_mfma_f32_16x16x32_bf16 v[82:85], v[54:57], v[86:89], v[82:85]
	ds_read_b128 v[86:89], v112 offset:17536
	s_waitcnt lgkmcnt(0)
	v_mfma_f32_16x16x32_bf16 v[82:85], v[58:61], v[86:89], v[82:85]
	ds_read_b128 v[86:89], v112 offset:21760
	s_waitcnt lgkmcnt(0)
	v_mfma_f32_16x16x32_bf16 v[86:89], v[50:53], v[86:89], 0
	v_mfma_f32_16x16x32_bf16 v[86:89], v[54:57], v[90:93], v[86:89]
	ds_read_b128 v[90:93], v112 offset:21888
	s_waitcnt lgkmcnt(0)
	v_mfma_f32_16x16x32_bf16 v[86:89], v[58:61], v[90:93], v[86:89]
	ds_read_b128 v[90:93], v112 offset:26112
	s_waitcnt lgkmcnt(0)
	v_mfma_f32_16x16x32_bf16 v[90:93], v[50:53], v[90:93], 0
	v_mfma_f32_16x16x32_bf16 v[90:93], v[54:57], v[202:205], v[90:93]
	ds_read_b128 v[202:205], v112 offset:26240
	s_waitcnt lgkmcnt(0)
	v_mfma_f32_16x16x32_bf16 v[90:93], v[58:61], v[202:205], v[90:93]
	ds_read_b128 v[202:205], v112 offset:26304
	s_waitcnt lgkmcnt(0)
	v_mfma_f32_16x16x32_bf16 v[90:93], v[62:65], v[202:205], v[90:93]
	ds_read_b128 v[202:205], v112 offset:30464
	v_mfma_f32_16x16x32_bf16 v[66:69], v[50:53], v[66:69], 0
	s_waitcnt lgkmcnt(0)
	v_mfma_f32_16x16x32_bf16 v[50:53], v[50:53], v[202:205], 0
	ds_read_b128 v[202:205], v112 offset:30528
	s_waitcnt lgkmcnt(0)
	v_mfma_f32_16x16x32_bf16 v[50:53], v[54:57], v[202:205], v[50:53]
	ds_read_b128 v[54:57], v112 offset:30592
	s_waitcnt lgkmcnt(0)
	v_mfma_f32_16x16x32_bf16 v[50:53], v[58:61], v[54:57], v[50:53]
	ds_read_b128 v[54:57], v112 offset:30656
	s_waitcnt vmcnt(27)
	v_lshlrev_b32_e32 v112, 2, v145
	s_waitcnt lgkmcnt(0)
	v_mfma_f32_16x16x32_bf16 v[50:53], v[62:65], v[54:57], v[50:53]
	v_lshlrev_b32_e32 v54, 16, v140
	s_waitcnt vmcnt(19)
	v_add_f32_e32 v55, v161, v78
	v_mul_f32_e32 v54, v55, v54
	v_and_b32_e32 v55, 0xffff0000, v140
	v_add_f32_e32 v56, v161, v79
	v_or_b32_e32 v128, s0, v112
	v_mul_f32_e32 v55, v56, v55
	v_lshlrev_b32_e32 v56, 16, v141
	v_add_f32_e32 v57, v161, v80
	v_lshl_add_u64 v[142:143], s[70:71], 0, v[128:129]
	v_mul_f32_e32 v56, v57, v56
	v_and_b32_e32 v57, 0xffff0000, v141
	v_add_f32_e32 v58, v161, v81
	v_mov_b32_e32 v128, 0x43e00000
	v_mul_f32_e32 v57, v58, v57
	v_med3_f32 v54, v54, s1, v128
	v_med3_f32 v55, v55, s1, v128
	v_mov_b32_e32 v58, v129
	v_cvt_pk_fp8_f32 v58, v54, v55
	v_med3_f32 v54, v56, s1, v128
	v_med3_f32 v55, v57, s1, v128
	v_cvt_pk_fp8_f32 v58, v54, v55 op_sel:[0,0,1]
	v_lshlrev_b64 v[54:55], 11, v[136:137]
	v_lshl_add_u64 v[54:55], v[142:143], 0, v[54:55]
	v_lshlrev_b32_e32 v56, 16, v138
	s_waitcnt vmcnt(18)
; __device__ __forceinline__ float bf_lo(unsigned w) { return __uint_as_float(w << 16); }
; __device__ __forceinline__ unsigned pk4f8(float a, float b, float c, float d) { int p = __builtin_amdgcn_cvt_pk_fp8_f32(sat8(a), sat8(b), 0, false); p = __builtin_amdgcn_cvt_pk_fp8_f32(sat8(c), sat8(d), p, true); return (unsigned)p; }
; __device__ __forceinline__ float bf_hi(unsigned w) { return __uint_as_float(w & 0xffff0000u); }
; __device__ __forceinline__ void s5_xs_load(v4u (&xv)[8], const Args& a, const Ctx& C, int b, int g) {
;     const bf16* XBg = (const bf16*)(a.ws + WS_XB) + ((size_t)g * MP + (size_t)b * SEQ) * 16;
; #pragma unroll
;     for (int i = 0; i < 8; ++i) xv[i] = __builtin_nontemporal_load((const v4u*)(XBg + (size_t)(C.tid + 512 * i) * 8));
; }
; __device__ __forceinline__ void gmlp_compute(GmlpRegs& R, const Args& a, const Ctx& C, int c, int hd) {
;     ...
;     for (int nt = 0; nt < 8; ++nt) { const size_t row = T0 + 16 * nt + fr; const float bs = R.bsv[nt];
;         const float o0 = bf_lo(R.uq[nt].x) * (acc[nt][0] + bs), o1 = bf_hi(R.uq[nt].x) * (acc[nt][1] + bs);
;         const float o2 = bf_lo(R.uq[nt].y) * (acc[nt][2] + bs), o3 = bf_hi(R.uq[nt].y) * (acc[nt][3] + bs);
;         *(unsigned*)((unsigned char*)Y + row * DM + chs) = pk4f8(o0, o1, o2, o3); }
	v_add_f32_e32 v57, v160, v66
	global_store_dword v[54:55], v58, off
	v_mul_f32_e32 v56, v57, v56
	v_and_b32_e32 v57, 0xffff0000, v138
	v_add_f32_e32 v58, v160, v67
	v_mul_f32_e32 v57, v58, v57
	v_lshlrev_b32_e32 v58, 16, v139
	v_add_f32_e32 v59, v160, v68
	v_mul_f32_e32 v58, v59, v58
	v_and_b32_e32 v59, 0xffff0000, v139
	v_add_f32_e32 v60, v160, v69
	v_mul_f32_e32 v59, v60, v59
	v_med3_f32 v56, v56, s1, v128
	v_med3_f32 v57, v57, s1, v128
	v_mov_b32_e32 v60, v129
	v_cvt_pk_fp8_f32 v60, v56, v57
	v_med3_f32 v56, v58, s1, v128
	v_med3_f32 v57, v59, s1, v128
	s_waitcnt vmcnt(18)
	v_add_f32_e32 v58, v159, v71
	v_cvt_pk_fp8_f32 v60, v56, v57 op_sel:[0,0,1]
	v_add_co_u32_e64 v56, s[70:71], s2, v54
	v_add_f32_e32 v59, v159, v72
	s_nop 0
	v_addc_co_u32_e64 v57, s[70:71], 0, v55, s[70:71]
	global_store_dword v[56:57], v60, off
	v_lshlrev_b32_e32 v56, 16, v134
	v_add_f32_e32 v57, v159, v70
	v_mul_f32_e32 v56, v57, v56
	v_and_b32_e32 v57, 0xffff0000, v134
	v_mul_f32_e32 v57, v58, v57
	v_lshlrev_b32_e32 v58, 16, v135
	v_mul_f32_e32 v58, v59, v58
	v_and_b32_e32 v59, 0xffff0000, v135
	v_add_f32_e32 v60, v159, v73
	v_mul_f32_e32 v59, v60, v59
	v_med3_f32 v56, v56, s1, v128
	v_med3_f32 v57, v57, s1, v128
	v_mov_b32_e32 v60, v129
	v_cvt_pk_fp8_f32 v60, v56, v57
	v_med3_f32 v56, v58, s1, v128
	v_med3_f32 v57, v59, s1, v128
	s_waitcnt vmcnt(18)
	v_add_f32_e32 v58, v156, v75
	v_cvt_pk_fp8_f32 v60, v56, v57 op_sel:[0,0,1]
	v_add_co_u32_e64 v56, s[70:71], s33, v54
	v_add_f32_e32 v59, v156, v76
	s_nop 0
	v_addc_co_u32_e64 v57, s[70:71], 0, v55, s[70:71]
	global_store_dword v[56:57], v60, off
	v_lshlrev_b32_e32 v56, 16, v132
	v_add_f32_e32 v57, v156, v74
	v_mul_f32_e32 v56, v57, v56
	v_and_b32_e32 v57, 0xffff0000, v132
	v_mul_f32_e32 v57, v58, v57
	v_lshlrev_b32_e32 v58, 16, v133
	v_mul_f32_e32 v58, v59, v58
	v_and_b32_e32 v59, 0xffff0000, v133
	v_add_f32_e32 v60, v156, v77
	v_mul_f32_e32 v59, v60, v59
	v_med3_f32 v56, v56, s1, v128
	v_med3_f32 v57, v57, s1, v128
	v_mov_b32_e32 v60, v129
	v_cvt_pk_fp8_f32 v60, v56, v57
	v_med3_f32 v56, v58, s1, v128
	v_med3_f32 v57, v59, s1, v128
	s_waitcnt vmcnt(18)
	v_add_f32_e32 v58, v154, v83
	v_cvt_pk_fp8_f32 v60, v56, v57 op_sel:[0,0,1]
	v_add_co_u32_e64 v56, s[70:71], s74, v54
	v_add_f32_e32 v59, v154, v84
	s_nop 0
	v_addc_co_u32_e64 v57, s[70:71], 0, v55, s[70:71]
	global_store_dword v[56:57], v60, off
	v_lshlrev_b32_e32 v56, 16, v130
	v_add_f32_e32 v57, v154, v82
	v_mul_f32_e32 v56, v57, v56
	v_and_b32_e32 v57, 0xffff0000, v130
	v_mul_f32_e32 v57, v58, v57
	v_lshlrev_b32_e32 v58, 16, v131
	v_mul_f32_e32 v58, v59, v58
	v_and_b32_e32 v59, 0xffff0000, v131
	v_add_f32_e32 v60, v154, v85
	v_mul_f32_e32 v59, v60, v59
	v_med3_f32 v56, v56, s1, v128
	v_med3_f32 v57, v57, s1, v128
	v_mov_b32_e32 v60, v129
	v_cvt_pk_fp8_f32 v60, v56, v57
	v_med3_f32 v56, v58, s1, v128
	v_med3_f32 v57, v59, s1, v128
	s_waitcnt vmcnt(18)
	v_add_f32_e32 v58, v152, v87
	v_cvt_pk_fp8_f32 v60, v56, v57 op_sel:[0,0,1]
	v_add_co_u32_e64 v56, s[70:71], s75, v54
	v_add_f32_e32 v59, v152, v88
	s_nop 0
	v_addc_co_u32_e64 v57, s[70:71], 0, v55, s[70:71]
	global_store_dword v[56:57], v60, off
	v_lshlrev_b32_e32 v56, 16, v126
	v_add_f32_e32 v57, v152, v86
	v_mul_f32_e32 v56, v57, v56
	v_and_b32_e32 v57, 0xffff0000, v126
	v_mul_f32_e32 v57, v58, v57
	v_lshlrev_b32_e32 v58, 16, v127
	v_mul_f32_e32 v58, v59, v58
	v_and_b32_e32 v59, 0xffff0000, v127
	v_add_f32_e32 v60, v152, v89
	v_mul_f32_e32 v59, v60, v59
	v_med3_f32 v56, v56, s1, v128
	v_med3_f32 v57, v57, s1, v128
	v_mov_b32_e32 v60, v129
	v_cvt_pk_fp8_f32 v60, v56, v57
	v_med3_f32 v56, v58, s1, v128
	v_med3_f32 v57, v59, s1, v128
	s_waitcnt vmcnt(18)
	v_add_f32_e32 v58, v151, v91
	v_cvt_pk_fp8_f32 v60, v56, v57 op_sel:[0,0,1]
	v_add_co_u32_e64 v56, s[70:71], s76, v54
	v_add_f32_e32 v59, v151, v92
	s_nop 0
	v_addc_co_u32_e64 v57, s[70:71], 0, v55, s[70:71]
	global_store_dword v[56:57], v60, off
	v_lshlrev_b32_e32 v56, 16, v124
	v_add_f32_e32 v57, v151, v90
	v_mul_f32_e32 v56, v57, v56
	v_and_b32_e32 v57, 0xffff0000, v124
	v_mul_f32_e32 v57, v58, v57
	v_lshlrev_b32_e32 v58, 16, v125
	v_mul_f32_e32 v58, v59, v58
	v_and_b32_e32 v59, 0xffff0000, v125
	v_add_f32_e32 v60, v151, v93
	v_mul_f32_e32 v59, v60, v59
	v_med3_f32 v56, v56, s1, v128
	v_med3_f32 v57, v57, s1, v128
	v_mov_b32_e32 v60, v129
	v_cvt_pk_fp8_f32 v60, v56, v57
	v_med3_f32 v56, v58, s1, v128
	v_med3_f32 v57, v59, s1, v128
	s_waitcnt vmcnt(18)
	v_add_f32_e32 v50, v150, v50
	v_cvt_pk_fp8_f32 v60, v56, v57 op_sel:[0,0,1]
	v_add_co_u32_e64 v56, s[70:71], s77, v54
	v_add_f32_e32 v51, v150, v51
	s_nop 0
	v_addc_co_u32_e64 v57, s[70:71], 0, v55, s[70:71]
	global_store_dword v[56:57], v60, off
	v_lshlrev_b32_e32 v56, 16, v122
	v_mul_f32_e32 v50, v50, v56
	v_and_b32_e32 v56, 0xffff0000, v122
	v_mul_f32_e32 v51, v51, v56
	v_med3_f32 v50, v50, s1, v128
	v_med3_f32 v51, v51, s1, v128
	v_lshlrev_b32_e32 v56, 16, v123
	v_add_f32_e32 v52, v150, v52
	v_cvt_pk_fp8_f32 v129, v50, v51
	v_mul_f32_e32 v52, v52, v56
	v_and_b32_e32 v56, 0xffff0000, v123
	v_add_f32_e32 v53, v150, v53
	v_mul_f32_e32 v53, v53, v56
	v_med3_f32 v50, v52, s1, v128
	v_med3_f32 v51, v53, s1, v128
	v_cvt_pk_fp8_f32 v129, v50, v51 op_sel:[0,0,1]
	v_add_co_u32_e64 v50, s[70:71], s78, v54
	v_readlane_b32 s0, v249, 0
	s_nop 0
	v_addc_co_u32_e64 v51, s[70:71], 0, v55, s[70:71]
	s_ashr_i32 s70, s0, 6
	s_ashr_i32 s71, s70, 31
	s_and_b32 s0, s0, 63
	s_lshl_b64 s[80:81], s[70:71], 16
	s_add_u32 s79, s94, s80
	s_addc_u32 s80, s95, s81
	s_mul_i32 s81, s0, 0x42000
	s_add_u32 s79, s79, s81
	s_addc_u32 s81, s80, 0
	s_add_u32 s80, s79, 0xc200000
	global_store_dword v[50:51], v129, off
	s_addc_u32 s81, s81, 0
	v_lshlrev_b32_e32 v87, 4, v146
	v_lshlrev_b32_e32 v86, 4, v95
	v_lshlrev_b32_e32 v85, 4, v120
	v_lshlrev_b32_e32 v84, 4, v157
	v_lshlrev_b32_e32 v83, 4, v158
	v_lshlrev_b32_e32 v82, 4, v155
	global_load_dwordx4 v[74:77], v94, s[80:81] nt
	global_load_dwordx4 v[78:81], v87, s[80:81] nt
	global_load_dwordx4 v[70:73], v148, s[80:81] nt
	global_load_dwordx4 v[66:69], v86, s[80:81] nt
	global_load_dwordx4 v[58:61], v85, s[80:81] nt
	global_load_dwordx4 v[62:65], v84, s[80:81] nt
	global_load_dwordx4 v[50:53], v83, s[80:81] nt
	global_load_dwordx4 v[54:57], v82, s[80:81] nt
	s_nop 0
	v_cndmask_b32_e64 v26, v26, 0, s[68:69]
	v_cndmask_b32_e64 v27, 0, v27, s[4:5]
	v_cndmask_b32_e64 v28, v28, 0, s[6:7]
	v_cndmask_b32_e64 v29, v29, 0, s[8:9]
	v_cvt_pk_bf16_f32 v26, v26, v27
	v_cvt_pk_bf16_f32 v27, v28, v29
	v_add_u32_e32 v28, v164, v169
	s_waitcnt vmcnt(27)
	s_waitcnt vmcnt(26)
	s_waitcnt vmcnt(25)
	s_waitcnt vmcnt(24)
	s_barrier
; #define LAS __attribute__((address_space(3)))
; __device__ __forceinline__ unsigned pk2(float lo, float hi) { return pg8::cvt_pk_bf16(lo, hi); }
; __device__ __forceinline__ void gmlp_compute(GmlpRegs& R, const Args& a, const Ctx& C, int c, int hd) {
;     ...
;     for (int i = 0; i < 8; ++i) { const int idx = tid + 512 * i, tr = idx >> 5, c4 = (idx & 31) * 4; f32x4 x = R.wv[i];
; #pragma unroll
;         for (int j = 0; j < 4; ++j) x[j] = (c4 + j <= tr) ? x[j] : 0.f;
;         *(LAS v2u*)(WL + tr * 272 + c4 * 2) = (v2u){pk2(x[0], x[1]), pk2(x[2], x[3])}; }
; #pragma unroll
;     for (int i = 0; i < 4; ++i) { const int idx = tid + 512 * i; LAS unsigned* d = (LAS unsigned*)(VL + (idx >> 4) * 260 + (idx & 15) * 16); d[0] = R.vv[i].x; d[1] = R.vv[i].y; d[2] = R.vv[i].z; d[3] = R.vv[i].w; }
;     if (tid < 128) { const float mu = R.s1 * (1.0f / DA), var = R.s2 * (1.0f / DA) - mu * mu; ST[2 * tid] = mu; ST[2 * tid + 1] = __builtin_amdgcn_rsqf(var + EPS); }
	ds_write_b64 v28, v[26:27]
	v_cndmask_b32_e64 v26, v30, 0, s[10:11]
	v_cndmask_b32_e64 v27, 0, v31, s[14:15]
	v_cndmask_b32_e64 v28, v32, 0, s[16:17]
	v_cndmask_b32_e64 v29, v33, 0, s[18:19]
	v_cndmask_b32_e64 v18, v18, 0, s[20:21]
	v_cndmask_b32_e64 v19, 0, v19, s[22:23]
	v_cndmask_b32_e64 v20, v20, 0, s[24:25]
	v_cndmask_b32_e64 v21, v21, 0, s[26:27]
	v_cvt_pk_bf16_f32 v26, v26, v27
	v_cvt_pk_bf16_f32 v27, v28, v29
	v_add_u32_e32 v28, v164, v170
	v_cvt_pk_bf16_f32 v18, v18, v19
	v_cvt_pk_bf16_f32 v19, v20, v21
	v_add_u32_e32 v20, v164, v171
	ds_write_b64 v28, v[26:27]
	ds_write_b64 v20, v[18:19]
	v_cndmask_b32_e64 v18, v22, 0, s[72:73]
	v_cndmask_b32_e64 v19, 0, v23, s[28:29]
	v_cndmask_b32_e64 v20, v24, 0, s[30:31]
	v_cndmask_b32_e64 v21, v25, 0, s[34:35]
	v_cndmask_b32_e64 v10, v10, 0, s[36:37]
	v_cndmask_b32_e64 v11, 0, v11, s[38:39]
	v_cndmask_b32_e64 v12, v12, 0, s[40:41]
	v_cndmask_b32_e64 v13, v13, 0, s[42:43]
	v_cvt_pk_bf16_f32 v18, v18, v19
	v_cvt_pk_bf16_f32 v19, v20, v21
	v_add_u32_e32 v20, v164, v172
	v_cvt_pk_bf16_f32 v10, v10, v11
	v_cvt_pk_bf16_f32 v11, v12, v13
	v_add_u32_e32 v12, v164, v173
	ds_write_b64 v20, v[18:19]
	ds_write_b64 v12, v[10:11]
	v_cndmask_b32_e64 v10, v14, 0, s[44:45]
	v_cndmask_b32_e64 v11, 0, v15, s[46:47]
	v_cndmask_b32_e64 v12, v16, 0, s[48:49]
	v_cndmask_b32_e64 v13, v17, 0, s[50:51]
	v_cndmask_b32_e64 v6, v6, 0, s[52:53]
	v_cndmask_b32_e64 v7, 0, v7, s[54:55]
	v_cndmask_b32_e64 v8, v8, 0, s[56:57]
	v_cndmask_b32_e64 v9, v9, 0, s[58:59]
	v_cndmask_b32_e64 v2, v2, 0, s[60:61]
	v_cndmask_b32_e64 v3, 0, v3, s[62:63]
	v_cndmask_b32_e64 v4, v4, 0, s[64:65]
	v_cndmask_b32_e64 v5, v5, 0, s[66:67]
	v_cvt_pk_bf16_f32 v10, v10, v11
	v_cvt_pk_bf16_f32 v11, v12, v13
	v_add_u32_e32 v12, v164, v174
	v_cvt_pk_bf16_f32 v6, v6, v7
	v_cvt_pk_bf16_f32 v7, v8, v9
	v_add_u32_e32 v8, v164, v176
	v_cvt_pk_bf16_f32 v2, v2, v3
	v_cvt_pk_bf16_f32 v3, v4, v5
	v_add_u32_e32 v4, v164, v178
	ds_write_b64 v12, v[10:11]
	ds_write_b64 v8, v[6:7]
	ds_write_b64 v4, v[2:3]
	v_add_u32_e32 v2, v175, v179
	v_add_u32_e32 v3, 0x8800, v2
	v_add_u32_e32 v2, 0x8808, v2
	ds_write2_b32 v2, v40, v41 offset1:1
	v_add_u32_e32 v2, v175, v180
	ds_write2_b32 v3, v38, v39 offset1:1
	v_add_u32_e32 v3, 0x8800, v2
	v_add_u32_e32 v2, 0x8808, v2
	ds_write2_b32 v2, v36, v37 offset1:1
	v_add_u32_e32 v2, v175, v181
	ds_write2_b32 v3, v34, v35 offset1:1
	v_add_u32_e32 v3, 0x8800, v2
	v_add_u32_e32 v2, 0x8808, v2
	ds_write2_b32 v2, v48, v49 offset1:1
	v_add_u32_e32 v2, v175, v182
	ds_write2_b32 v3, v46, v47 offset1:1
	v_add_u32_e32 v3, 0x8800, v2
	v_add_u32_e32 v2, 0x8808, v2
	ds_write2_b32 v3, v42, v43 offset1:1
	ds_write2_b32 v2, v44, v45 offset1:1
	s_and_saveexec_b64 s[4:5], vcc
	s_cbranch_execz .LBB0_973
	s_waitcnt vmcnt(24)
	v_mul_f32_e32 v113, 0x3a800000, v252
	v_mul_f32_e32 v121, 0x3a800000, v253
	v_fma_f32 v2, -v121, v121, v113
	v_add_f32_e32 v2, 0x358637bd, v2
	v_rsq_f32_e32 v3, v2
	v_add_u32_e32 v4, 0x10a00, v177
	v_mov_b32_e32 v2, v121
	ds_write_b64 v4, v[2:3]
